# split-phase barriers at seam 6 and after P9 rounds 0-1 (L2 write-back kept, cross-XCD wait moved to seam 7 / to the overlapped final-norm workgroups only); overlapped final norm takes tiles of its own
# baseline (speedup 1.0000x reference)
.LBB0_809:
	s_andn2_saveexec_b64 s[8:9], s[8:9]
	s_cbranch_execz .LBB0_827
	s_mov_b64 s[8:9], exec
	buffer_wbl2 sc1
	s_waitcnt lgkmcnt(0)
	s_waitcnt vmcnt(0)
	v_mbcnt_lo_u32_b32 v1, s8, 0
	v_mbcnt_hi_u32_b32 v1, s9, v1
	v_cmp_eq_u32_e32 vcc, 0, v1
	s_and_saveexec_b64 s[10:11], vcc
	s_cbranch_execz .LBB0_812
	s_bcnt1_i32_b64 s3, s[8:9]
	v_mov_b32_e32 v2, 0x1e03000
	v_mov_b32_e32 v3, s3
	global_atomic_add v2, v2, v3, s[78:79] offset:1024 sc0
.LBB0_812:
	s_or_b64 exec, exec, s[10:11]
	v_cvt_f32_u32_e32 v3, v0
	s_waitcnt vmcnt(0)
	v_readfirstlane_b32 s3, v2
	s_add_u32 s10, s78, 0x1e03500
	s_addc_u32 s11, s79, 0
	v_rcp_iflag_f32_e32 v3, v3
	v_add_u32_e32 v1, s3, v1
	v_add_u32_e32 v4, 1, v1
	s_mov_b64 s[12:13], -1
	v_mul_f32_e32 v2, 0x4f7ffffe, v3
	v_cvt_u32_f32_e32 v2, v2
	v_sub_u32_e32 v3, 0, v0
	v_mul_lo_u32 v3, v3, v2
	v_mul_hi_u32 v3, v2, v3
	v_add_u32_e32 v2, v2, v3
	v_mul_hi_u32 v2, v1, v2
	v_mul_lo_u32 v3, v2, v0
	v_sub_u32_e32 v1, v1, v3
	v_add_u32_e32 v5, 1, v2
	v_cmp_ge_u32_e32 vcc, v1, v0
	v_sub_u32_e32 v3, v1, v0
	s_nop 0
	v_cndmask_b32_e32 v2, v2, v5, vcc
	v_cndmask_b32_e32 v1, v1, v3, vcc
	v_add_u32_e32 v3, 1, v2
	v_cmp_ge_u32_e32 vcc, v1, v0
	s_nop 1
	v_cndmask_b32_e32 v2, v2, v3, vcc
	v_mul_lo_u32 v1, v0, v2
	v_add_u32_e32 v0, v1, v0
	v_cmp_ne_u32_e32 vcc, v4, v0
	v_mov_b64_e32 v[0:1], s[10:11]
	s_and_saveexec_b64 s[8:9], vcc
	s_cbranch_execz .LBB0_824
	v_readlane_b32 s3, v255, 0
	s_cmp_eq_u32 s3, 0
	s_cbranch_scc1 .LBB0_826
	v_mov_b32_e32 v0, 0
	global_load_dword v1, v0, s[10:11] sc1
	s_mov_b64 s[16:17], 0
	s_waitcnt vmcnt(0)
	v_cmp_eq_u32_e32 vcc, v1, v2
	s_and_saveexec_b64 s[14:15], vcc
	s_cbranch_execz .LBB0_823
	s_add_u32 s12, s78, 0x1e00200
	s_addc_u32 s13, s79, 0
	s_mov_b32 s3, 1
	s_branch .LBB0_816

.LBB0_936:
	s_or_b64 exec, exec, s[12:13]
	v_cvt_f32_u32_e32 v3, v0
	s_waitcnt vmcnt(0)
	v_readfirstlane_b32 s3, v2
	s_add_u32 s12, s78, 0x1e03500
	s_addc_u32 s13, s79, 0
	v_rcp_iflag_f32_e32 v3, v3
	v_add_u32_e32 v1, s3, v1
	v_add_u32_e32 v4, 1, v1
	s_mov_b64 s[14:15], -1
	v_mul_f32_e32 v2, 0x4f7ffffe, v3
	v_cvt_u32_f32_e32 v2, v2
	v_sub_u32_e32 v3, 0, v0
	v_mul_lo_u32 v3, v3, v2
	v_mul_hi_u32 v3, v2, v3
	v_add_u32_e32 v2, v2, v3
	v_mul_hi_u32 v2, v1, v2
	v_mul_lo_u32 v3, v2, v0
	v_sub_u32_e32 v1, v1, v3
	v_add_u32_e32 v5, 1, v2
	v_cmp_ge_u32_e32 vcc, v1, v0
	v_sub_u32_e32 v3, v1, v0
	s_nop 0
	v_cndmask_b32_e32 v2, v2, v5, vcc
	v_cndmask_b32_e32 v1, v1, v3, vcc
	v_add_u32_e32 v3, 1, v2
	v_cmp_ge_u32_e32 vcc, v1, v0
	s_nop 1
	v_cndmask_b32_e32 v2, v2, v3, vcc
	v_mul_lo_u32 v1, v0, v2
	v_add_u32_e32 v0, v1, v0
	v_cmp_ne_u32_e32 vcc, v4, v0
	v_mov_b64_e32 v[0:1], s[12:13]
	s_and_saveexec_b64 s[10:11], vcc
	s_cbranch_execz .LBB0_948
	v_readlane_b32 s3, v255, 0
	s_cmp_eq_u32 s3, 0
	s_cbranch_scc1 .LBB0_950
	v_mov_b32_e32 v0, 0
	global_load_dword v1, v0, s[12:13] sc1
	s_mov_b64 s[18:19], 0
	s_waitcnt vmcnt(0)
	v_cmp_eq_u32_e32 vcc, v1, v2
	s_and_saveexec_b64 s[16:17], vcc
	s_cbranch_execz .LBB0_947
	s_add_u32 s14, s78, 0x1e00200
	s_addc_u32 s15, s79, 0
	s_mov_b32 s3, 1
	s_branch .LBB0_940

.Lp10a:
	s_add_u32 s4, s78, 0x1e03500
	s_addc_u32 s5, s79, 0
	v_mov_b32_e32 v20, 0
.Lw10:
	global_load_dword v21, v20, s[4:5] sc1
	s_waitcnt vmcnt(0)
	v_readfirstlane_b32 s10, v21
	s_cmp_ge_u32 s10, 5
	s_cbranch_scc1 .Lw10d
	s_sleep 1
	s_branch .Lw10
.Lw10d:
	v_readlane_b32 s2, v254, 6
	v_readlane_b32 s3, v254, 7
	v_and_b32_e32 v0, 63, v210
	v_readfirstlane_b32 s0, v210
	v_lshlrev_b32_e32 v1, 3, v0
	v_lshlrev_b32_e32 v2, 4, v0
	v_mov_b32_e32 v3, 0x3a800000
	v_mov_b32_e32 v121, 0x358637bd
	s_lshr_b32 s0, s0, 6
	global_load_dwordx4 v[4:7], v2, s[2:3]
	global_load_dwordx4 v[8:11], v2, s[2:3] offset:1024
	global_load_dwordx4 v[12:15], v2, s[2:3] offset:2048
	global_load_dwordx4 v[16:19], v2, s[2:3] offset:3072
	s_sub_i32 s1, s101, 128
	s_and_b32 s4, s1, 7
	s_lshr_b32 s5, s1, 4
	s_cmp_lt_u32 s4, 4
	s_cselect_b32 s4, 4, 0xff
	s_cmp_eq_u32 s5, s4
	s_cbranch_scc1 .Lp10a_done
	s_and_b32 s4, s1, 7
	s_mul_i32 s4, s4, 20
	s_lshr_b32 s5, s1, 3
	s_add_i32 s4, s4, s5
	s_lshl_b32 s4, s4, 8
	s_cmp_gt_u32 s0, 1
	s_cbranch_scc1 .Lp10a_done
	s_lshl_b32 s5, s0, 7
	s_add_i32 s4, s4, s5
	s_movk_i32 s10, 32
	s_lshl_b32 s5, s4, 11
	s_add_u32 s12, s78, s5
	s_addc_u32 s13, s79, 0
	s_add_u32 s12, s12, 0x2000000
	s_addc_u32 s13, s13, 0
	s_lshl_b32 s5, s4, 12
	s_add_u32 s14, s76, s5
	s_addc_u32 s15, s77, 0
